# v51 + backward direction: the 4 forward-output rows prefetched at the start of the output stage; one vmcnt(0) in the store stage
# speedup vs baseline: 1.0073x; 1.0013x over previous
.LBB0_974:
	s_and_b64 vcc, exec, s[46:47]
	s_cbranch_vccz .Lret_nopf
	s_add_u32 s16, s40, s28
	s_addc_u32 s17, s41, s34
	s_lshl_b64 s[16:17], s[16:17], 12
	s_or_b32 s16, s16, s80
	s_add_u32 s16, s26, s16
	s_addc_u32 s17, s27, s17
	s_mov_b32 s58, 0xfffe0000
	s_mov_b32 s59, -1
	v_sub_u32_e32 v2, 0x7f, v197
	v_lshl_or_b32 v2, v2, 11, v203
	v_ashrrev_i32_e32 v3, 31, v2
	v_lshl_add_u64 v[2:3], v[2:3], 1, s[16:17]
	global_load_dwordx4 v[124:127], v[2:3], off
	v_lshl_add_u64 v[2:3], v[2:3], 0, s[58:59]
	global_load_dwordx4 v[128:131], v[2:3], off
	v_lshl_add_u64 v[2:3], v[2:3], 0, s[58:59]
	global_load_dwordx4 v[132:135], v[2:3], off
	v_lshl_add_u64 v[2:3], v[2:3], 0, s[58:59]
	global_load_dwordx4 v[136:139], v[2:3], off

.Lret_f_end:
	s_nop 3
	v_add_u32_e32 v1, v234, v207
	v_add_u32_e32 v10, 1, v1
	v_cvt_f32_i32_e32 v14, v10
	v_mul_f32_e32 v2, v232, v14
	v_exp_f32_e32 v4, v2
	v_lshlrev_b32_e32 v2, 3, v233
	v_mul_lo_u32 v3, v1, s68
	v_add3_u32 v5, v208, v2, v3
	v_mul_f32_e32 v2, v4, v96
	v_mul_f32_e32 v3, v4, v97
	v_cvt_pk_bf16_f32 v2, v2, v3
	v_mul_f32_e32 v3, v4, v98
	v_mul_f32_e32 v6, v4, v99
	v_cvt_pk_bf16_f32 v3, v3, v6
	v_add_u32_e32 v1, 33, v1
	ds_write_b64 v5, v[2:3] offset:34816
	v_mul_f32_e32 v2, v4, v100
	v_mul_f32_e32 v3, v4, v101
	v_cvt_f32_i32_e32 v1, v1
	v_cvt_pk_bf16_f32 v2, v2, v3
	v_mul_f32_e32 v3, v4, v102
	v_mul_f32_e32 v6, v4, v103
	v_cvt_pk_bf16_f32 v3, v3, v6
	ds_write_b64 v5, v[2:3] offset:34832
	v_mul_f32_e32 v2, v4, v104
	v_mul_f32_e32 v3, v4, v105
	v_cvt_pk_bf16_f32 v2, v2, v3
	v_mul_f32_e32 v3, v4, v106
	v_mul_f32_e32 v1, v232, v1
	v_mul_f32_e32 v6, v4, v107
	v_cvt_pk_bf16_f32 v3, v3, v6
	v_exp_f32_e32 v1, v1
	ds_write_b64 v5, v[2:3] offset:34848
	v_mul_f32_e32 v2, v4, v108
	v_mul_f32_e32 v3, v4, v109
	v_cvt_pk_bf16_f32 v2, v2, v3
	v_mul_f32_e32 v3, v4, v110
	v_mul_f32_e32 v4, v4, v111
	v_cvt_pk_bf16_f32 v3, v3, v4
	ds_write_b64 v5, v[2:3] offset:34864
	v_mul_f32_e32 v2, v1, v80
	v_mul_f32_e32 v3, v1, v81
	v_cvt_pk_bf16_f32 v2, v2, v3
	v_mul_f32_e32 v3, v1, v82
	v_mul_f32_e32 v4, v1, v83
	v_cvt_pk_bf16_f32 v3, v3, v4
	ds_write_b64 v5, v[2:3] offset:43520
	v_mul_f32_e32 v2, v1, v84
	v_mul_f32_e32 v3, v1, v85
	v_cvt_pk_bf16_f32 v2, v2, v3
	v_mul_f32_e32 v3, v1, v86
	v_mul_f32_e32 v4, v1, v87
	v_cvt_pk_bf16_f32 v3, v3, v4
	ds_write_b64 v5, v[2:3] offset:43536
	v_mul_f32_e32 v2, v1, v88
	v_mul_f32_e32 v3, v1, v89
	v_cvt_pk_bf16_f32 v2, v2, v3
	v_mul_f32_e32 v3, v1, v90
	s_add_u32 s16, s40, s28
	v_mul_f32_e32 v4, v1, v91
	v_cvt_pk_bf16_f32 v3, v3, v4
	s_addc_u32 s17, s41, s34
	ds_write_b64 v5, v[2:3] offset:43552
	v_mul_f32_e32 v2, v1, v92
	v_mul_f32_e32 v3, v1, v93
	s_lshl_b64 s[18:19], s[16:17], 12
	v_cvt_pk_bf16_f32 v2, v2, v3
	v_mul_f32_e32 v3, v1, v94
	s_or_b32 s18, s18, s80
	v_mul_f32_e32 v1, v1, v95
	v_cvt_pk_bf16_f32 v3, v3, v1
	s_add_u32 s56, s26, s18
	ds_write_b64 v5, v[2:3] offset:43568
	s_waitcnt lgkmcnt(0)
	s_barrier
	s_addc_u32 s57, s27, s19
	v_sub_u32_e32 v10, 0x7f, v197
	ds_read_b128 v[2:5], v228 offset:34816
	s_add_u32 s54, s64, s18
	v_cndmask_b32_e64 v1, v10, v197, s[44:45]
	s_addc_u32 s55, s65, s19
	s_lshl_b64 s[16:17], s[16:17], 5
	v_lshl_or_b32 v8, v1, 11, v203
	s_add_u32 s18, s78, s16
	v_ashrrev_i32_e32 v9, 31, v8
	s_addc_u32 s19, s79, s17
	v_lshl_add_u64 v[6:7], v[8:9], 1, s[56:57]
	s_mov_b64 s[16:17], -1
	s_and_b64 vcc, exec, s[46:47]
	v_mbcnt_hi_u32_b32 v1, -1, v226
	s_cbranch_vccz .LBB0_982
	v_lshl_add_u64 v[8:9], v[8:9], 1, s[54:55]
	s_waitcnt lgkmcnt(0)
	v_lshlrev_b32_e32 v80, 16, v2
	v_and_b32_e32 v81, 0xffff0000, v2
	v_lshlrev_b32_e32 v82, 16, v3
	v_and_b32_e32 v83, 0xffff0000, v3
	v_lshlrev_b32_e32 v84, 16, v4
	v_and_b32_e32 v85, 0xffff0000, v4
	v_lshlrev_b32_e32 v86, 16, v5
	v_and_b32_e32 v87, 0xffff0000, v5
	s_waitcnt vmcnt(0)
	v_lshlrev_b32_e32 v88, 16, v124
	v_and_b32_e32 v89, 0xffff0000, v124
	v_lshlrev_b32_e32 v90, 16, v125
	v_and_b32_e32 v91, 0xffff0000, v125
	v_lshlrev_b32_e32 v92, 16, v126
	v_and_b32_e32 v93, 0xffff0000, v126
	v_lshlrev_b32_e32 v94, 16, v127
	v_and_b32_e32 v95, 0xffff0000, v127
	v_add_f32_e32 v80, v88, v80
	v_add_f32_e32 v81, v89, v81
	v_add_f32_e32 v82, v90, v82
	v_add_f32_e32 v83, v91, v83
	v_add_f32_e32 v84, v92, v84
	v_add_f32_e32 v85, v93, v85
	v_add_f32_e32 v86, v94, v86
	v_add_f32_e32 v87, v95, v87
	v_lshlrev_b32_e32 v94, 3, v10
	v_ashrrev_i32_e32 v95, 31, v94
	v_lshl_add_u64 v[94:95], v[94:95], 2, s[18:19]
	v_add_f32_e32 v88, v80, v81
	v_add_f32_e32 v89, v82, v83
	v_add_f32_e32 v90, v84, v85
	v_add_f32_e32 v91, v86, v87
	v_mul_f32_e32 v12, v80, v80
	v_mul_f32_e32 v13, v82, v82
	v_mul_f32_e32 v14, v84, v84
	v_mul_f32_e32 v15, v86, v86
	v_add_f32_e32 v88, v88, v89
	v_add_f32_e32 v90, v90, v91
	v_fmac_f32_e32 v12, v81, v81
	v_fmac_f32_e32 v13, v83, v83
	v_fmac_f32_e32 v14, v85, v85
	v_fmac_f32_e32 v15, v87, v87
	v_add_f32_e32 v92, v88, v90
	v_add_f32_e32 v12, v12, v13
	v_add_f32_e32 v14, v14, v15
	v_add_f32_e32 v93, v12, v14
	v_cvt_pk_bf16_f32 v80, v80, v81
	v_cvt_pk_bf16_f32 v81, v82, v83
	v_cvt_pk_bf16_f32 v82, v84, v85
	v_cvt_pk_bf16_f32 v83, v86, v87
	v_add_f32_dpp v92, v92, v92 quad_perm:[1,0,3,2] row_mask:0xf bank_mask:0xf
	v_add_f32_dpp v93, v93, v93 quad_perm:[1,0,3,2] row_mask:0xf bank_mask:0xf
	s_nop 0
	v_add_f32_dpp v92, v92, v92 quad_perm:[2,3,0,1] row_mask:0xf bank_mask:0xf
	v_add_f32_dpp v93, v93, v93 quad_perm:[2,3,0,1] row_mask:0xf bank_mask:0xf
	s_nop 0
	v_add_f32_dpp v92, v92, v92 row_ror:4 row_mask:0xf bank_mask:0xf
	v_add_f32_dpp v93, v93, v93 row_ror:4 row_mask:0xf bank_mask:0xf
	s_nop 0
	v_add_f32_dpp v92, v92, v92 row_ror:8 row_mask:0xf bank_mask:0xf
	v_add_f32_dpp v93, v93, v93 row_ror:8 row_mask:0xf bank_mask:0xf
	s_nop 0
	global_store_dwordx4 v[8:9], v[80:83], off
	s_and_saveexec_b64 s[16:17], s[8:9]
	s_cbranch_execz .LBB0_981
	global_atomic_add_f32 v[94:95], v92, off
	global_atomic_add_f32 v[94:95], v93, off offset:4

.LBB0_984:
	v_sub_u32_e32 v10, 0x5f, v197
	s_waitcnt lgkmcnt(0)
	v_cndmask_b32_e64 v2, v10, v231, s[44:45]
	v_lshl_or_b32 v8, v2, 11, v203
	ds_read_b128 v[2:5], v228 offset:43520
	v_ashrrev_i32_e32 v9, 31, v8
	v_cndmask_b32_e64 v11, 0, 1, s[46:47]
	v_lshl_add_u64 v[6:7], v[8:9], 1, s[56:57]
	v_cmp_ne_u32_e64 s[16:17], 1, v11
	s_andn2_b64 vcc, exec, s[46:47]
	s_mov_b64 s[58:59], -1
	s_cbranch_vccnz .LBB0_988
	v_lshl_add_u64 v[8:9], v[8:9], 1, s[54:55]
	s_waitcnt lgkmcnt(0)
	v_lshlrev_b32_e32 v80, 16, v2
	v_and_b32_e32 v81, 0xffff0000, v2
	v_lshlrev_b32_e32 v82, 16, v3
	v_and_b32_e32 v83, 0xffff0000, v3
	v_lshlrev_b32_e32 v84, 16, v4
	v_and_b32_e32 v85, 0xffff0000, v4
	v_lshlrev_b32_e32 v86, 16, v5
	v_and_b32_e32 v87, 0xffff0000, v5
	v_lshlrev_b32_e32 v88, 16, v128
	v_and_b32_e32 v89, 0xffff0000, v128
	v_lshlrev_b32_e32 v90, 16, v129
	v_and_b32_e32 v91, 0xffff0000, v129
	v_lshlrev_b32_e32 v92, 16, v130
	v_and_b32_e32 v93, 0xffff0000, v130
	v_lshlrev_b32_e32 v94, 16, v131
	v_and_b32_e32 v95, 0xffff0000, v131
	v_add_f32_e32 v80, v88, v80
	v_add_f32_e32 v81, v89, v81
	v_add_f32_e32 v82, v90, v82
	v_add_f32_e32 v83, v91, v83
	v_add_f32_e32 v84, v92, v84
	v_add_f32_e32 v85, v93, v85
	v_add_f32_e32 v86, v94, v86
	v_add_f32_e32 v87, v95, v87
	v_lshlrev_b32_e32 v94, 3, v10
	v_ashrrev_i32_e32 v95, 31, v94
	v_lshl_add_u64 v[94:95], v[94:95], 2, s[18:19]
	v_add_f32_e32 v88, v80, v81
	v_add_f32_e32 v89, v82, v83
	v_add_f32_e32 v90, v84, v85
	v_add_f32_e32 v91, v86, v87
	v_mul_f32_e32 v12, v80, v80
	v_mul_f32_e32 v13, v82, v82
	v_mul_f32_e32 v14, v84, v84
	v_mul_f32_e32 v15, v86, v86
	v_add_f32_e32 v88, v88, v89
	v_add_f32_e32 v90, v90, v91
	v_fmac_f32_e32 v12, v81, v81
	v_fmac_f32_e32 v13, v83, v83
	v_fmac_f32_e32 v14, v85, v85
	v_fmac_f32_e32 v15, v87, v87
	v_add_f32_e32 v92, v88, v90
	v_add_f32_e32 v12, v12, v13
	v_add_f32_e32 v14, v14, v15
	v_add_f32_e32 v93, v12, v14
	v_cvt_pk_bf16_f32 v80, v80, v81
	v_cvt_pk_bf16_f32 v81, v82, v83
	v_cvt_pk_bf16_f32 v82, v84, v85
	v_cvt_pk_bf16_f32 v83, v86, v87
	v_add_f32_dpp v92, v92, v92 quad_perm:[1,0,3,2] row_mask:0xf bank_mask:0xf
	v_add_f32_dpp v93, v93, v93 quad_perm:[1,0,3,2] row_mask:0xf bank_mask:0xf
	s_nop 0
	v_add_f32_dpp v92, v92, v92 quad_perm:[2,3,0,1] row_mask:0xf bank_mask:0xf
	v_add_f32_dpp v93, v93, v93 quad_perm:[2,3,0,1] row_mask:0xf bank_mask:0xf
	s_nop 0
	v_add_f32_dpp v92, v92, v92 row_ror:4 row_mask:0xf bank_mask:0xf
	v_add_f32_dpp v93, v93, v93 row_ror:4 row_mask:0xf bank_mask:0xf
	s_nop 0
	v_add_f32_dpp v92, v92, v92 row_ror:8 row_mask:0xf bank_mask:0xf
	v_add_f32_dpp v93, v93, v93 row_ror:8 row_mask:0xf bank_mask:0xf
	s_nop 0
	global_store_dwordx4 v[8:9], v[80:83], off
	s_and_saveexec_b64 s[58:59], s[8:9]
	s_cbranch_execz .LBB0_987
	global_atomic_add_f32 v[94:95], v92, off
	global_atomic_add_f32 v[94:95], v93, off offset:4

.LBB0_990:
	v_sub_u32_e32 v10, 63, v197
	s_waitcnt lgkmcnt(0)
	v_cndmask_b32_e64 v2, v10, v230, s[44:45]
	v_lshl_or_b32 v8, v2, 11, v203
	ds_read_b128 v[2:5], v228 offset:52224
	v_ashrrev_i32_e32 v9, 31, v8
	v_lshl_add_u64 v[6:7], v[8:9], 1, s[56:57]
	s_and_b64 vcc, exec, s[16:17]
	s_mov_b64 s[58:59], -1
	s_cbranch_vccnz .LBB0_994
	v_lshl_add_u64 v[8:9], v[8:9], 1, s[54:55]
	s_waitcnt lgkmcnt(0)
	v_lshlrev_b32_e32 v80, 16, v2
	v_and_b32_e32 v81, 0xffff0000, v2
	v_lshlrev_b32_e32 v82, 16, v3
	v_and_b32_e32 v83, 0xffff0000, v3
	v_lshlrev_b32_e32 v84, 16, v4
	v_and_b32_e32 v85, 0xffff0000, v4
	v_lshlrev_b32_e32 v86, 16, v5
	v_and_b32_e32 v87, 0xffff0000, v5
	v_lshlrev_b32_e32 v88, 16, v132
	v_and_b32_e32 v89, 0xffff0000, v132
	v_lshlrev_b32_e32 v90, 16, v133
	v_and_b32_e32 v91, 0xffff0000, v133
	v_lshlrev_b32_e32 v92, 16, v134
	v_and_b32_e32 v93, 0xffff0000, v134
	v_lshlrev_b32_e32 v94, 16, v135
	v_and_b32_e32 v95, 0xffff0000, v135
	v_add_f32_e32 v80, v88, v80
	v_add_f32_e32 v81, v89, v81
	v_add_f32_e32 v82, v90, v82
	v_add_f32_e32 v83, v91, v83
	v_add_f32_e32 v84, v92, v84
	v_add_f32_e32 v85, v93, v85
	v_add_f32_e32 v86, v94, v86
	v_add_f32_e32 v87, v95, v87
	v_lshlrev_b32_e32 v94, 3, v10
	v_ashrrev_i32_e32 v95, 31, v94
	v_lshl_add_u64 v[94:95], v[94:95], 2, s[18:19]
	v_add_f32_e32 v88, v80, v81
	v_add_f32_e32 v89, v82, v83
	v_add_f32_e32 v90, v84, v85
	v_add_f32_e32 v91, v86, v87
	v_mul_f32_e32 v12, v80, v80
	v_mul_f32_e32 v13, v82, v82
	v_mul_f32_e32 v14, v84, v84
	v_mul_f32_e32 v15, v86, v86
	v_add_f32_e32 v88, v88, v89
	v_add_f32_e32 v90, v90, v91
	v_fmac_f32_e32 v12, v81, v81
	v_fmac_f32_e32 v13, v83, v83
	v_fmac_f32_e32 v14, v85, v85
	v_fmac_f32_e32 v15, v87, v87
	v_add_f32_e32 v92, v88, v90
	v_add_f32_e32 v12, v12, v13
	v_add_f32_e32 v14, v14, v15
	v_add_f32_e32 v93, v12, v14
	v_cvt_pk_bf16_f32 v80, v80, v81
	v_cvt_pk_bf16_f32 v81, v82, v83
	v_cvt_pk_bf16_f32 v82, v84, v85
	v_cvt_pk_bf16_f32 v83, v86, v87
	v_add_f32_dpp v92, v92, v92 quad_perm:[1,0,3,2] row_mask:0xf bank_mask:0xf
	v_add_f32_dpp v93, v93, v93 quad_perm:[1,0,3,2] row_mask:0xf bank_mask:0xf
	s_nop 0
	v_add_f32_dpp v92, v92, v92 quad_perm:[2,3,0,1] row_mask:0xf bank_mask:0xf
	v_add_f32_dpp v93, v93, v93 quad_perm:[2,3,0,1] row_mask:0xf bank_mask:0xf
	s_nop 0
	v_add_f32_dpp v92, v92, v92 row_ror:4 row_mask:0xf bank_mask:0xf
	v_add_f32_dpp v93, v93, v93 row_ror:4 row_mask:0xf bank_mask:0xf
	s_nop 0
	v_add_f32_dpp v92, v92, v92 row_ror:8 row_mask:0xf bank_mask:0xf
	v_add_f32_dpp v93, v93, v93 row_ror:8 row_mask:0xf bank_mask:0xf
	s_nop 0
	global_store_dwordx4 v[8:9], v[80:83], off
	s_and_saveexec_b64 s[58:59], s[8:9]
	s_cbranch_execz .LBB0_993
	global_atomic_add_f32 v[94:95], v92, off
	global_atomic_add_f32 v[94:95], v93, off offset:4

.LBB0_996:
	v_sub_u32_e32 v10, 31, v197
	s_waitcnt lgkmcnt(0)
	v_cndmask_b32_e64 v2, v10, v229, s[44:45]
	v_lshl_or_b32 v8, v2, 11, v203
	ds_read_b128 v[2:5], v228 offset:60928
	v_ashrrev_i32_e32 v9, 31, v8
	v_lshl_add_u64 v[6:7], v[8:9], 1, s[56:57]
	s_and_b64 vcc, exec, s[16:17]
	s_mov_b64 s[16:17], -1
	s_cbranch_vccnz .LBB0_1000
	v_lshl_add_u64 v[8:9], v[8:9], 1, s[54:55]
	s_waitcnt lgkmcnt(0)
	v_lshlrev_b32_e32 v80, 16, v2
	v_and_b32_e32 v81, 0xffff0000, v2
	v_lshlrev_b32_e32 v82, 16, v3
	v_and_b32_e32 v83, 0xffff0000, v3
	v_lshlrev_b32_e32 v84, 16, v4
	v_and_b32_e32 v85, 0xffff0000, v4
	v_lshlrev_b32_e32 v86, 16, v5
	v_and_b32_e32 v87, 0xffff0000, v5
	v_lshlrev_b32_e32 v88, 16, v136
	v_and_b32_e32 v89, 0xffff0000, v136
	v_lshlrev_b32_e32 v90, 16, v137
	v_and_b32_e32 v91, 0xffff0000, v137
	v_lshlrev_b32_e32 v92, 16, v138
	v_and_b32_e32 v93, 0xffff0000, v138
	v_lshlrev_b32_e32 v94, 16, v139
	v_and_b32_e32 v95, 0xffff0000, v139
	v_add_f32_e32 v80, v88, v80
	v_add_f32_e32 v81, v89, v81
	v_add_f32_e32 v82, v90, v82
	v_add_f32_e32 v83, v91, v83
	v_add_f32_e32 v84, v92, v84
	v_add_f32_e32 v85, v93, v85
	v_add_f32_e32 v86, v94, v86
	v_add_f32_e32 v87, v95, v87
	v_lshlrev_b32_e32 v94, 3, v10
	v_ashrrev_i32_e32 v95, 31, v94
	v_lshl_add_u64 v[94:95], v[94:95], 2, s[18:19]
	v_add_f32_e32 v88, v80, v81
	v_add_f32_e32 v89, v82, v83
	v_add_f32_e32 v90, v84, v85
	v_add_f32_e32 v91, v86, v87
	v_mul_f32_e32 v12, v80, v80
	v_mul_f32_e32 v13, v82, v82
	v_mul_f32_e32 v14, v84, v84
	v_mul_f32_e32 v15, v86, v86
	v_add_f32_e32 v88, v88, v89
	v_add_f32_e32 v90, v90, v91
	v_fmac_f32_e32 v12, v81, v81
	v_fmac_f32_e32 v13, v83, v83
	v_fmac_f32_e32 v14, v85, v85
	v_fmac_f32_e32 v15, v87, v87
	v_add_f32_e32 v92, v88, v90
	v_add_f32_e32 v12, v12, v13
	v_add_f32_e32 v14, v14, v15
	v_add_f32_e32 v93, v12, v14
	v_cvt_pk_bf16_f32 v80, v80, v81
	v_cvt_pk_bf16_f32 v81, v82, v83
	v_cvt_pk_bf16_f32 v82, v84, v85
	v_cvt_pk_bf16_f32 v83, v86, v87
	v_add_f32_dpp v92, v92, v92 quad_perm:[1,0,3,2] row_mask:0xf bank_mask:0xf
	v_add_f32_dpp v93, v93, v93 quad_perm:[1,0,3,2] row_mask:0xf bank_mask:0xf
	s_nop 0
	v_add_f32_dpp v92, v92, v92 quad_perm:[2,3,0,1] row_mask:0xf bank_mask:0xf
	v_add_f32_dpp v93, v93, v93 quad_perm:[2,3,0,1] row_mask:0xf bank_mask:0xf
	s_nop 0
	v_add_f32_dpp v92, v92, v92 row_ror:4 row_mask:0xf bank_mask:0xf
	v_add_f32_dpp v93, v93, v93 row_ror:4 row_mask:0xf bank_mask:0xf
	s_nop 0
	v_add_f32_dpp v92, v92, v92 row_ror:8 row_mask:0xf bank_mask:0xf
	v_add_f32_dpp v93, v93, v93 row_ror:8 row_mask:0xf bank_mask:0xf
	s_nop 0
	global_store_dwordx4 v[8:9], v[80:83], off
	s_and_saveexec_b64 s[16:17], s[8:9]
	s_cbranch_execz .LBB0_999
	global_atomic_add_f32 v[94:95], v92, off
	global_atomic_add_f32 v[94:95], v93, off offset:4
